# adds bit-exact removal of never-taken denormal/inf guards in GLA gate log-sigmoid
# speedup vs baseline: 1.0818x; 1.0077x over previous
.LBB0_334:
	s_waitcnt vmcnt(10)
	v_perm_b32 v2, v70, v66, s33
	v_perm_b32 v66, v70, v66, s72
	ds_write2_b32 v168, v2, v66 offset1:32
	v_perm_b32 v2, v71, v67, s33
	ds_write_b32 v169, v2 offset:24576
	v_perm_b32 v2, v71, v67, s72
	ds_write_b32 v170, v2 offset:24576
	v_perm_b32 v2, v72, v68, s33
	ds_write_b32 v171, v2 offset:24576
	v_perm_b32 v2, v72, v68, s72
	ds_write_b32 v172, v2 offset:24576
	v_perm_b32 v2, v73, v69, s33
	ds_write_b32 v173, v2 offset:24576
	v_perm_b32 v2, v73, v69, s72
	ds_write_b32 v174, v2 offset:24576
	s_waitcnt vmcnt(9)
	v_perm_b32 v2, v62, v58, s33
	v_perm_b32 v58, v62, v58, s72
	ds_write2_b32 v175, v2, v58 offset1:32
	v_perm_b32 v2, v63, v59, s33
	ds_write_b32 v176, v2 offset:24576
	v_perm_b32 v2, v63, v59, s72
	ds_write_b32 v177, v2 offset:24576
	v_perm_b32 v2, v64, v60, s33
	ds_write_b32 v178, v2 offset:24576
	v_perm_b32 v2, v64, v60, s72
	ds_write_b32 v179, v2 offset:24576
	v_perm_b32 v2, v65, v61, s33
	ds_write_b32 v180, v2 offset:24576
	v_perm_b32 v2, v65, v61, s72
	s_and_b64 vcc, exec, s[4:5]
	v_mov_b64_e32 v[90:91], v[108:109]
	v_mov_b64_e32 v[96:97], v[108:109]
	v_mov_b64_e32 v[94:95], v[116:117]
	v_mov_b64_e32 v[92:93], v[118:119]
	v_mov_b32_e32 v211, v117
	v_mov_b32_e32 v215, v117
	v_mov_b32_e32 v219, v117
	v_mov_b32_e32 v210, v116
	v_mov_b32_e32 v135, v119
	v_mov_b32_e32 v209, v118
	v_mov_b32_e32 v214, v116
	v_mov_b32_e32 v212, v119
	v_mov_b32_e32 v213, v118
	v_mov_b32_e32 v218, v116
	v_mov_b32_e32 v216, v119
	v_mov_b32_e32 v217, v118
	ds_write_b32 v181, v2 offset:24576
	s_cbranch_vccnz .LBB0_303
	s_waitcnt vmcnt(8)
	v_cndmask_b32_e64 v57, 0, v57, s[10:11]
	v_cndmask_b32_e64 v56, 0, v56, s[10:11]
	v_cndmask_b32_e64 v55, 0, v55, s[10:11]
	v_cndmask_b32_e64 v54, 0, v54, s[10:11]
	s_nop 1
	v_mfma_f32_16x16x32_bf16 v[58:61], v[54:57], v[6:9], 0
	v_mfma_f32_16x16x32_bf16 v[62:65], v[54:57], v[10:13], 0
	s_nop 6
	v_add_f32_e32 v2, v111, v58
	v_min_f32_e32 v67, 0, v2
	v_mul_f32_e64 v2, |v2|, s73
	v_exp_f32_e32 v2, v2
	s_nop 0
	v_add_f32_e32 v2, 1.0, v2
	v_log_f32_e32 v2, v2
	s_nop 0
	v_mul_f32_e32 v58, 0x3f317217, v2
	v_fma_f32 v58, v2, s67, -v58
	v_fmac_f32_e32 v58, 0x3377d1cf, v2
	v_fmac_f32_e32 v58, 0x3f317217, v2
	v_mov_b32_e32 v2, v58
	v_mov_b32_e32 v58, 0
	v_sub_f32_e32 v69, v2, v58
	v_add_f32_e32 v2, v111, v59
	v_min_f32_e32 v58, 0, v2
	v_mul_f32_e64 v2, |v2|, s73
	v_exp_f32_e32 v2, v2
	s_nop 0
	v_add_f32_e32 v2, 1.0, v2
	v_log_f32_e32 v2, v2
	s_nop 0
	v_mul_f32_e32 v59, 0x3f317217, v2
	v_fma_f32 v59, v2, s67, -v59
	v_fmac_f32_e32 v59, 0x3377d1cf, v2
	v_fmac_f32_e32 v59, 0x3f317217, v2
	v_mov_b32_e32 v2, v59
	v_mov_b32_e32 v59, 0
	v_sub_f32_e32 v2, v2, v59
	v_sub_f32_e32 v70, v58, v2
	v_add_f32_e32 v2, v111, v60
	v_min_f32_e32 v58, 0, v2
	v_mul_f32_e64 v2, |v2|, s73
	v_exp_f32_e32 v2, v2
	s_nop 0
	v_add_f32_e32 v2, 1.0, v2
	v_log_f32_e32 v2, v2
	s_nop 0
	v_mul_f32_e32 v59, 0x3f317217, v2
	v_fma_f32 v59, v2, s67, -v59
	v_fmac_f32_e32 v59, 0x3377d1cf, v2
	v_fmac_f32_e32 v59, 0x3f317217, v2
	v_mov_b32_e32 v2, v59
	v_mov_b32_e32 v59, 0
	v_sub_f32_e32 v2, v2, v59
	v_sub_f32_e32 v71, v58, v2
	v_add_f32_e32 v2, v111, v61
	v_min_f32_e32 v58, 0, v2
	v_mul_f32_e64 v2, |v2|, s73
	v_exp_f32_e32 v2, v2
	s_nop 0
	v_add_f32_e32 v2, 1.0, v2
	v_log_f32_e32 v2, v2
	s_nop 0
	v_mul_f32_e32 v59, 0x3f317217, v2
	v_fma_f32 v59, v2, s67, -v59
	v_fmac_f32_e32 v59, 0x3377d1cf, v2
	v_fmac_f32_e32 v59, 0x3f317217, v2
	v_mov_b32_e32 v2, v59
	v_mov_b32_e32 v59, 0
	v_sub_f32_e32 v2, v2, v59
	v_sub_f32_e32 v72, v58, v2
	v_add_f32_e32 v2, v139, v62
	v_min_f32_e32 v66, 0, v2
	v_mul_f32_e64 v2, |v2|, s73
	v_exp_f32_e32 v2, v2
	v_and_b32_e32 v62, 64, v1
	v_add_f32_e32 v2, 1.0, v2
	v_log_f32_e32 v2, v2
	s_nop 0
	v_mul_f32_e32 v58, 0x3f317217, v2
	v_fma_f32 v58, v2, s67, -v58
	v_fmac_f32_e32 v58, 0x3377d1cf, v2
	v_fmac_f32_e32 v58, 0x3f317217, v2
	v_mov_b32_e32 v2, v58
	v_mov_b32_e32 v58, 0
	v_sub_f32_e32 v68, v2, v58
	v_add_u32_e32 v2, -16, v1
	v_pk_add_f32 v[58:59], v[66:67], v[68:69] neg_lo:[0,1] neg_hi:[0,1]
	v_cmp_lt_i32_e32 vcc, v2, v62
	v_subrev_u32_e32 v66, 32, v1
	v_pk_mul_f32 v[90:91], v[58:59], s[96:97] op_sel_hi:[1,0]
	v_cndmask_b32_e32 v2, v2, v1, vcc
	v_cmp_lt_i32_e32 vcc, v66, v62
	v_fmamk_f32 v94, v70, 0x3d800000, v91
	v_fmamk_f32 v93, v71, 0x3d800000, v94
	v_cndmask_b32_e32 v66, v66, v1, vcc
	v_lshlrev_b32_e32 v67, 2, v66
	v_subrev_u32_e32 v66, 48, v1
	v_cmp_lt_i32_e32 vcc, v66, v62
	v_lshlrev_b32_e32 v2, 2, v2
	v_or_b32_e32 v62, v62, v166
	v_cndmask_b32_e32 v66, v66, v1, vcc
	v_fmamk_f32 v92, v72, 0x3d800000, v93
	v_lshlrev_b32_e32 v68, 2, v66
	v_lshlrev_b32_e32 v66, 2, v62
	ds_bpermute_b32 v62, v2, v92
	ds_bpermute_b32 v69, v67, v92
	ds_bpermute_b32 v70, v68, v92
	v_mfma_f32_16x16x32_bf16 v[58:61], v[54:57], v[14:17], 0
	s_waitcnt lgkmcnt(2)
	v_cndmask_b32_e64 v62, v62, 0, s[6:7]
	s_waitcnt lgkmcnt(1)
	v_cndmask_b32_e64 v69, 0, v69, s[12:13]
	v_add_f32_e32 v62, v62, v69
	s_waitcnt lgkmcnt(0)
	v_cndmask_b32_e64 v69, 0, v70, s[8:9]
	v_add_f32_e32 v95, v62, v69
	v_add_f32_e32 v62, v95, v92
	ds_bpermute_b32 v62, v66, v62
	v_mfma_f32_16x16x32_bf16 v[54:57], v[54:57], v[18:21], 0
	s_and_saveexec_b64 s[0:1], s[6:7]
	s_cbranch_execz .LBB0_337
	s_waitcnt lgkmcnt(0)
	ds_write_b32 v167, v62
.LBB0_337:
	s_or_b64 exec, exec, s[0:1]
	s_waitcnt lgkmcnt(0)
	v_add_f32_e32 v62, v139, v63
	v_min_f32_e32 v63, 0, v62
	v_mul_f32_e64 v62, |v62|, s73
	v_exp_f32_e32 v62, v62
	s_nop 0
	v_add_f32_e32 v62, 1.0, v62
	v_log_f32_e32 v62, v62
	s_nop 0
	v_mul_f32_e32 v69, 0x3f317217, v62
	v_fma_f32 v69, v62, s67, -v69
	v_fmac_f32_e32 v69, 0x3377d1cf, v62
	v_fmac_f32_e32 v69, 0x3f317217, v62
	v_mov_b32_e32 v62, v69
	v_mov_b32_e32 v69, 0
	v_sub_f32_e32 v62, v62, v69
	v_sub_f32_e32 v62, v63, v62
	v_add_f32_e32 v63, v139, v64
	v_min_f32_e32 v64, 0, v63
	v_mul_f32_e64 v63, |v63|, s73
	v_exp_f32_e32 v63, v63
	v_fmamk_f32 v210, v62, 0x3d800000, v90
	v_add_f32_e32 v63, 1.0, v63
	v_log_f32_e32 v63, v63
	s_nop 0
	v_mul_f32_e32 v69, 0x3f317217, v63
	v_fma_f32 v69, v63, s67, -v69
	v_fmac_f32_e32 v69, 0x3377d1cf, v63
	v_fmac_f32_e32 v69, 0x3f317217, v63
	v_mov_b32_e32 v63, v69
	v_mov_b32_e32 v69, 0
	v_sub_f32_e32 v63, v63, v69
	v_sub_f32_e32 v63, v64, v63
	v_add_f32_e32 v64, v139, v65
	v_min_f32_e32 v65, 0, v64
	v_mul_f32_e64 v64, |v64|, s73
	v_exp_f32_e32 v64, v64
	v_fmamk_f32 v135, v63, 0x3d800000, v210
	v_add_f32_e32 v64, 1.0, v64
	v_log_f32_e32 v64, v64
	s_nop 0
	v_mul_f32_e32 v69, 0x3f317217, v64
	v_fma_f32 v69, v64, s67, -v69
	v_fmac_f32_e32 v69, 0x3377d1cf, v64
	v_fmac_f32_e32 v69, 0x3f317217, v64
	v_mov_b32_e32 v64, v69
	v_mov_b32_e32 v69, 0
	v_sub_f32_e32 v64, v64, v69
	v_sub_f32_e32 v64, v65, v64
	v_fmamk_f32 v209, v64, 0x3d800000, v135
	ds_bpermute_b32 v62, v2, v209
	ds_bpermute_b32 v63, v67, v209
	ds_bpermute_b32 v64, v68, v209
	s_waitcnt lgkmcnt(2)
	v_cndmask_b32_e64 v62, v62, 0, s[6:7]
	s_waitcnt lgkmcnt(1)
	v_cndmask_b32_e64 v63, 0, v63, s[12:13]
	v_add_f32_e32 v62, v62, v63
	s_waitcnt lgkmcnt(0)
	v_cndmask_b32_e64 v63, 0, v64, s[8:9]
	v_add_f32_e32 v211, v62, v63
	v_add_f32_e32 v62, v209, v211
	ds_bpermute_b32 v62, v66, v62
	s_and_saveexec_b64 s[0:1], s[6:7]
	s_cbranch_execz .LBB0_339
	s_waitcnt lgkmcnt(0)
	ds_write_b32 v167, v62 offset:64
.LBB0_339:
	s_or_b64 exec, exec, s[0:1]
	v_add_f32_e32 v58, v140, v58
	v_min_f32_e32 v63, 0, v58
	v_mul_f32_e64 v58, |v58|, s73
	v_exp_f32_e32 v58, v58
	v_add_f32_e32 v54, v141, v54
	v_add_f32_e32 v58, 1.0, v58
	s_waitcnt lgkmcnt(0)
	s_nop 0
	v_log_f32_e32 v58, v58
	s_nop 0
	v_mul_f32_e32 v62, 0x3f317217, v58
	v_fma_f32 v62, v58, s67, -v62
	v_fmac_f32_e32 v62, 0x3377d1cf, v58
	v_fmac_f32_e32 v62, 0x3f317217, v58
	v_mov_b32_e32 v58, v62
	v_mov_b32_e32 v62, 0
	v_sub_f32_e32 v65, v58, v62
	v_add_f32_e32 v58, v140, v59
	v_min_f32_e32 v59, 0, v58
	v_mul_f32_e64 v58, |v58|, s73
	v_exp_f32_e32 v58, v58
	s_nop 0
	v_add_f32_e32 v58, 1.0, v58
	v_log_f32_e32 v58, v58
	s_nop 0
	v_mul_f32_e32 v62, 0x3f317217, v58
	v_fma_f32 v62, v58, s67, -v62
	v_fmac_f32_e32 v62, 0x3377d1cf, v58
	v_fmac_f32_e32 v62, 0x3f317217, v58
	v_mov_b32_e32 v58, v62
	v_mov_b32_e32 v62, 0
	v_sub_f32_e32 v58, v58, v62
	v_sub_f32_e32 v69, v59, v58
	v_add_f32_e32 v58, v140, v60
	v_min_f32_e32 v59, 0, v58
	v_mul_f32_e64 v58, |v58|, s73
	v_exp_f32_e32 v58, v58
	v_min_f32_e32 v62, 0, v54
	v_mul_f32_e64 v54, |v54|, s73
	v_exp_f32_e32 v54, v54
	v_add_f32_e32 v58, 1.0, v58
	v_add_f32_e32 v54, 1.0, v54
	s_nop 0
	v_log_f32_e32 v58, v58
	s_nop 0
	v_mul_f32_e32 v60, 0x3f317217, v58
	v_fma_f32 v60, v58, s67, -v60
	v_fmac_f32_e32 v60, 0x3377d1cf, v58
	v_fmac_f32_e32 v60, 0x3f317217, v58
	v_mov_b32_e32 v58, v60
	v_mov_b32_e32 v60, 0
	v_sub_f32_e32 v58, v58, v60
	v_sub_f32_e32 v60, v59, v58
	v_add_f32_e32 v58, v140, v61
	v_min_f32_e32 v59, 0, v58
	v_mul_f32_e64 v58, |v58|, s73
	v_exp_f32_e32 v58, v58
	s_nop 0
	v_add_f32_e32 v58, 1.0, v58
	v_log_f32_e32 v58, v58
	s_nop 0
	v_mul_f32_e32 v61, 0x3f317217, v58
	v_fma_f32 v61, v58, s67, -v61
	v_fmac_f32_e32 v61, 0x3377d1cf, v58
	v_fmac_f32_e32 v61, 0x3f317217, v58
	v_mov_b32_e32 v58, v61
	v_mov_b32_e32 v61, 0
	v_sub_f32_e32 v58, v58, v61
	v_sub_f32_e32 v61, v59, v58
	s_nop 0
	v_log_f32_e32 v54, v54
	s_nop 0
	v_mul_f32_e32 v58, 0x3f317217, v54
	v_fma_f32 v58, v54, s67, -v58
	v_fmac_f32_e32 v58, 0x3377d1cf, v54
	v_fmac_f32_e32 v58, 0x3f317217, v54
	v_mov_b32_e32 v54, v58
	v_mov_b32_e32 v58, 0
	v_sub_f32_e32 v64, v54, v58
	v_pk_add_f32 v[58:59], v[62:63], v[64:65] neg_lo:[0,1] neg_hi:[0,1]
	s_nop 0
	v_pk_mul_f32 v[96:97], v[58:59], s[96:97] op_sel_hi:[1,0]
	s_nop 0
	v_fmamk_f32 v214, v69, 0x3d800000, v97
	v_fmamk_f32 v212, v60, 0x3d800000, v214
	v_fmamk_f32 v213, v61, 0x3d800000, v212
	ds_bpermute_b32 v54, v2, v213
	ds_bpermute_b32 v58, v67, v213
	ds_bpermute_b32 v59, v68, v213
	s_waitcnt lgkmcnt(2)
	v_cndmask_b32_e64 v54, v54, 0, s[6:7]
	s_waitcnt lgkmcnt(1)
	v_cndmask_b32_e64 v58, 0, v58, s[12:13]
	v_add_f32_e32 v54, v54, v58
	s_waitcnt lgkmcnt(0)
	v_cndmask_b32_e64 v58, 0, v59, s[8:9]
	v_add_f32_e32 v215, v54, v58
	v_add_f32_e32 v54, v213, v215
	ds_bpermute_b32 v54, v66, v54
	s_and_saveexec_b64 s[0:1], s[6:7]
	s_cbranch_execz .LBB0_341
	s_waitcnt lgkmcnt(0)
	ds_write_b32 v167, v54 offset:128
.LBB0_341:
	s_or_b64 exec, exec, s[0:1]
	s_waitcnt lgkmcnt(0)
	v_add_f32_e32 v54, v141, v55
	v_min_f32_e32 v55, 0, v54
	v_mul_f32_e64 v54, |v54|, s73
	v_exp_f32_e32 v54, v54
	s_nop 0
	v_add_f32_e32 v54, 1.0, v54
	v_log_f32_e32 v54, v54
	s_nop 0
	v_mul_f32_e32 v58, 0x3f317217, v54
	v_fma_f32 v58, v54, s67, -v58
	v_fmac_f32_e32 v58, 0x3377d1cf, v54
	v_fmac_f32_e32 v58, 0x3f317217, v54
	v_mov_b32_e32 v54, v58
	v_mov_b32_e32 v58, 0
	v_sub_f32_e32 v54, v54, v58
	v_sub_f32_e32 v54, v55, v54
	v_add_f32_e32 v55, v141, v56
	v_min_f32_e32 v56, 0, v55
	v_mul_f32_e64 v55, |v55|, s73
	v_exp_f32_e32 v55, v55
	v_fmamk_f32 v218, v54, 0x3d800000, v96
	v_add_f32_e32 v55, 1.0, v55
	v_log_f32_e32 v55, v55
	s_nop 0
	v_mul_f32_e32 v58, 0x3f317217, v55
	v_fma_f32 v58, v55, s67, -v58
	v_fmac_f32_e32 v58, 0x3377d1cf, v55
	v_fmac_f32_e32 v58, 0x3f317217, v55
	v_mov_b32_e32 v55, v58
	v_mov_b32_e32 v58, 0
	v_sub_f32_e32 v55, v55, v58
	v_sub_f32_e32 v55, v56, v55
	v_add_f32_e32 v56, v141, v57
	v_min_f32_e32 v57, 0, v56
	v_mul_f32_e64 v56, |v56|, s73
	v_exp_f32_e32 v56, v56
	v_fmamk_f32 v216, v55, 0x3d800000, v218
	v_add_f32_e32 v56, 1.0, v56
	v_log_f32_e32 v56, v56
	s_nop 0
	v_mul_f32_e32 v58, 0x3f317217, v56
	v_fma_f32 v58, v56, s67, -v58
	v_fmac_f32_e32 v58, 0x3377d1cf, v56
	v_fmac_f32_e32 v58, 0x3f317217, v56
	v_mov_b32_e32 v56, v58
	v_mov_b32_e32 v58, 0
	v_sub_f32_e32 v56, v56, v58
	v_sub_f32_e32 v56, v57, v56
	v_fmamk_f32 v217, v56, 0x3d800000, v216
	ds_bpermute_b32 v2, v2, v217
	ds_bpermute_b32 v54, v67, v217
	ds_bpermute_b32 v55, v68, v217
	s_waitcnt lgkmcnt(2)
	v_cndmask_b32_e64 v2, v2, 0, s[6:7]
	s_waitcnt lgkmcnt(1)
	v_cndmask_b32_e64 v54, 0, v54, s[12:13]
	v_add_f32_e32 v2, v2, v54
	s_waitcnt lgkmcnt(0)
	v_cndmask_b32_e64 v54, 0, v55, s[8:9]
	v_add_f32_e32 v219, v2, v54
	v_add_f32_e32 v2, v217, v219
	ds_bpermute_b32 v2, v66, v2
	s_and_saveexec_b64 s[0:1], s[6:7]
	s_cbranch_execz .LBB0_302
	s_waitcnt lgkmcnt(0)
	ds_write_b32 v167, v2 offset:192
	s_branch .LBB0_302
